# skinny projection (end of phase 4): nt hint on its normalized-row loads (those rows are not read again for ~400 us)
# speedup vs baseline: 1.0048x; 1.0048x over previous
.LBB0_562:
	s_ashr_i32 s67, s66, 31
	s_lshl_b64 s[0:1], s[66:67], 18
	v_readlane_b32 s2, v253, 52
	v_readlane_b32 s3, v253, 53
	s_add_u32 s0, s2, s0
	v_and_b32_e32 v2, 0x7c00, v146
	s_addc_u32 s1, s3, s1
	v_lshlrev_b32_e32 v24, 1, v2
	v_mov_b32_e32 v25, 0
	v_lshl_add_u64 v[2:3], s[0:1], 0, v[24:25]
	v_and_b32_e32 v54, 0xf0, v147
	v_mov_b32_e32 v55, v25
	s_mov_b32 s2, 0xfc00
	v_mov_b32_e32 v6, 0x8000
	v_lshl_add_u64 v[18:19], v[2:3], 0, v[54:55]
	v_bitop3_b32 v6, v146, s2, v6 bitop3:0xc8
	s_mov_b32 s2, 0x20000
	v_lshlrev_b32_e32 v6, 1, v6
	v_mov_b32_e32 v7, v25
	v_add_co_u32_e32 v10, vcc, s2, v18
	s_mov_b32 s2, 0x1fc00
	v_mov_b32_e32 v14, 0x18000
	v_lshl_add_u64 v[6:7], s[0:1], 0, v[6:7]
	v_bitop3_b32 v14, v146, s2, v14 bitop3:0xc8
	s_waitcnt vmcnt(0)
	s_barrier
	global_load_dwordx4 v[2:5], v[18:19], off nt
	v_lshl_add_u64 v[20:21], v[6:7], 0, v[54:55]
	v_lshlrev_b32_e32 v14, 1, v14
	v_mov_b32_e32 v15, v25
	v_lshl_add_u64 v[24:25], s[78:79], 0, v[24:25]
	global_load_dwordx4 v[6:9], v[20:21], off nt
	v_addc_co_u32_e32 v11, vcc, 0, v19, vcc
	v_lshl_add_u64 v[14:15], s[0:1], 0, v[14:15]
	v_lshl_add_u64 v[24:25], v[24:25], 0, v[54:55]
	s_mov_b32 s0, 0x2900000
	global_load_dwordx4 v[10:13], v[10:11], off nt
	v_lshl_add_u64 v[22:23], v[14:15], 0, v[54:55]
	v_add_co_u32_e32 v26, vcc, s0, v24
	global_load_dwordx4 v[14:17], v[22:23], off nt
	s_nop 0
	v_addc_co_u32_e32 v27, vcc, 0, v25, vcc
	global_load_dwordx4 v[30:33], v[26:27], off
	s_mov_b64 s[0:1], 0x20000
	v_lshl_add_u64 v[26:27], v[18:19], 0, s[0:1]
	s_mov_b64 s[0:1], 0x2900000
	v_lshl_add_u64 v[24:25], v[24:25], 0, s[0:1]
	global_load_dwordx4 v[34:37], v[18:19], off offset:256 nt
	global_load_dwordx4 v[38:41], v[20:21], off offset:256 nt
	global_load_dwordx4 v[42:45], v[26:27], off offset:256 nt
	global_load_dwordx4 v[46:49], v[22:23], off offset:256 nt
	global_load_dwordx4 v[50:53], v[24:25], off offset:256
	v_lshrrev_b32_e32 v55, 4, v0
	v_or_b32_e32 v56, 0x200, v0
	v_or_b32_e32 v57, 0x600, v0
	v_mul_u32_u24_e32 v55, 0x110, v55
	v_lshrrev_b32_e32 v56, 4, v56
	v_lshrrev_b32_e32 v57, 4, v57
	v_readlane_b32 s1, v253, 0
	v_and_b32_e32 v28, 31, v0
	v_add3_u32 v82, 0, v55, v54
	v_mul_u32_u24_e32 v55, 0x110, v56
	v_mul_u32_u24_e32 v56, 0x110, v57
	s_bfe_u32 s0, s1, 0x20006
	s_lshr_b32 s1, s1, 8
	v_lshrrev_b32_e32 v29, 5, v177
	v_add3_u32 v83, 0, v55, v54
	v_add3_u32 v84, 0, v56, v54
	v_lshl_or_b32 v54, s0, 5, v28
	s_lshl_b32 s2, s1, 7
	v_lshlrev_b32_e32 v58, 4, v29
	v_mul_u32_u24_e32 v54, 0x110, v54
	s_add_i32 s2, s2, 0
	v_add3_u32 v85, s2, v54, v58
	v_add_u32_e32 v87, 0x13200, v82
	s_cmp_lg_u32 s1, 1
	s_waitcnt vmcnt(9)
	ds_write_b128 v82, v[2:5]
	s_waitcnt vmcnt(8)
	ds_write_b128 v83, v[6:9]
	s_waitcnt vmcnt(7)
	ds_write_b128 v82, v[10:13] offset:17408
	s_waitcnt vmcnt(6)
	ds_write_b128 v84, v[14:17]
	s_waitcnt vmcnt(5)
	ds_write_b128 v82, v[30:33] offset:34816
	s_waitcnt lgkmcnt(0)
	s_waitcnt lgkmcnt(0)
	s_barrier
	ds_read_b128 v[2:5], v85
	v_mul_u32_u24_e32 v6, 0x110, v28
	v_add3_u32 v86, s2, v6, v58
	ds_read_b128 v[6:9], v86 offset:34816
	ds_read_b128 v[30:33], v85 offset:32
	ds_read_b128 v[54:57], v86 offset:34848
	s_waitcnt lgkmcnt(2)
	v_mfma_f32_32x32x16_bf16 v[2:17], v[2:5], v[6:9], 0
	ds_read_b128 v[58:61], v85 offset:64
	ds_read_b128 v[62:65], v85 offset:96
	ds_read_b128 v[66:69], v86 offset:34880
	ds_read_b128 v[70:73], v86 offset:34912
	s_waitcnt vmcnt(4)
	ds_write_b128 v82, v[34:37] offset:43520
	s_waitcnt vmcnt(3)
	ds_write_b128 v83, v[38:41] offset:43520
	s_waitcnt vmcnt(2)
	ds_write_b128 v82, v[42:45] offset:60928
	s_waitcnt vmcnt(1)
	ds_write_b128 v84, v[46:49] offset:43520
	s_waitcnt vmcnt(0)
	ds_write_b128 v87, v[50:53]
	v_add_u32_e32 v88, 0xaa00, v86
	s_waitcnt lgkmcnt(9)
	v_mfma_f32_32x32x16_bf16 v[2:17], v[30:33], v[54:57], v[2:17]
	global_load_dwordx4 v[30:33], v[18:19], off offset:512 nt
	global_load_dwordx4 v[34:37], v[20:21], off offset:512 nt
	global_load_dwordx4 v[38:41], v[26:27], off offset:512 nt
	global_load_dwordx4 v[42:45], v[22:23], off offset:512 nt
	global_load_dwordx4 v[46:49], v[24:25], off offset:512
	s_waitcnt lgkmcnt(0)
	s_waitcnt lgkmcnt(0)
	s_barrier
	ds_read_b128 v[50:53], v85 offset:43520
	v_mfma_f32_32x32x16_bf16 v[2:17], v[58:61], v[66:69], v[2:17]
	v_mfma_f32_32x32x16_bf16 v[2:17], v[62:65], v[70:73], v[2:17]
	ds_read_b128 v[54:57], v88 offset:34816
	ds_read_b128 v[58:61], v85 offset:43552
	ds_read_b128 v[62:65], v88 offset:34848
	s_waitcnt lgkmcnt(2)
	v_mfma_f32_32x32x16_bf16 v[2:17], v[50:53], v[54:57], v[2:17]
	ds_read_b128 v[50:53], v85 offset:43584
	s_waitcnt lgkmcnt(1)
	v_mfma_f32_32x32x16_bf16 v[2:17], v[58:61], v[62:65], v[2:17]
	ds_read_b128 v[54:57], v85 offset:43616
	ds_read_b128 v[58:61], v88 offset:34880
	ds_read_b128 v[62:65], v88 offset:34912
	global_load_dwordx4 v[66:69], v[18:19], off offset:768 nt
	global_load_dwordx4 v[70:73], v[20:21], off offset:768 nt
	global_load_dwordx4 v[74:77], v[26:27], off offset:768 nt
	global_load_dwordx4 v[78:81], v[22:23], off offset:768 nt
	s_waitcnt lgkmcnt(1)
	v_mfma_f32_32x32x16_bf16 v[2:17], v[50:53], v[58:61], v[2:17]
	global_load_dwordx4 v[50:53], v[24:25], off offset:768
	s_waitcnt vmcnt(9)
	ds_write_b128 v82, v[30:33]
	s_waitcnt vmcnt(8)
	ds_write_b128 v83, v[34:37]
	s_waitcnt vmcnt(7)
	ds_write_b128 v82, v[38:41] offset:17408
	s_waitcnt vmcnt(6)
	ds_write_b128 v84, v[42:45]
	s_waitcnt vmcnt(5)
	ds_write_b128 v82, v[46:49] offset:34816
	s_waitcnt lgkmcnt(5)
	v_mfma_f32_32x32x16_bf16 v[2:17], v[54:57], v[62:65], v[2:17]
	s_waitcnt lgkmcnt(0)
	s_waitcnt lgkmcnt(0)
	s_barrier
	ds_read_b128 v[30:33], v85
	ds_read_b128 v[34:37], v86 offset:34816
	ds_read_b128 v[38:41], v85 offset:32
	ds_read_b128 v[42:45], v86 offset:34848
	s_waitcnt lgkmcnt(2)
	v_mfma_f32_32x32x16_bf16 v[2:17], v[30:33], v[34:37], v[2:17]
	ds_read_b128 v[30:33], v85 offset:64
	ds_read_b128 v[34:37], v85 offset:96
	ds_read_b128 v[46:49], v86 offset:34880
	ds_read_b128 v[54:57], v86 offset:34912
	s_waitcnt vmcnt(4)
	ds_write_b128 v82, v[66:69] offset:43520
	s_waitcnt vmcnt(3)
	ds_write_b128 v83, v[70:73] offset:43520
	s_waitcnt vmcnt(2)
	ds_write_b128 v82, v[74:77] offset:60928
	s_waitcnt vmcnt(1)
	ds_write_b128 v84, v[78:81] offset:43520
	s_waitcnt vmcnt(0)
	ds_write_b128 v87, v[50:53]
	s_waitcnt lgkmcnt(9)
	v_mfma_f32_32x32x16_bf16 v[2:17], v[38:41], v[42:45], v[2:17]
	global_load_dwordx4 v[38:41], v[18:19], off offset:1024 nt
	global_load_dwordx4 v[42:45], v[20:21], off offset:1024 nt
	s_waitcnt lgkmcnt(6)
	v_mfma_f32_32x32x16_bf16 v[2:17], v[30:33], v[46:49], v[2:17]
	global_load_dwordx4 v[30:33], v[26:27], off offset:1024 nt
	global_load_dwordx4 v[46:49], v[22:23], off offset:1024 nt
	global_load_dwordx4 v[50:53], v[24:25], off offset:1024
	s_waitcnt lgkmcnt(0)
	s_waitcnt lgkmcnt(0)
	s_barrier
	v_mfma_f32_32x32x16_bf16 v[2:17], v[34:37], v[54:57], v[2:17]
	ds_read_b128 v[34:37], v85 offset:43520
	ds_read_b128 v[54:57], v88 offset:34816
	ds_read_b128 v[58:61], v85 offset:43552
	ds_read_b128 v[62:65], v88 offset:34848
	s_waitcnt lgkmcnt(2)
	v_mfma_f32_32x32x16_bf16 v[2:17], v[34:37], v[54:57], v[2:17]
	ds_read_b128 v[34:37], v85 offset:43584
	s_waitcnt lgkmcnt(1)
	v_mfma_f32_32x32x16_bf16 v[2:17], v[58:61], v[62:65], v[2:17]
	global_load_dwordx4 v[54:57], v[18:19], off offset:1280 nt
	global_load_dwordx4 v[58:61], v[20:21], off offset:1280 nt
	ds_read_b128 v[62:65], v88 offset:34880
	ds_read_b128 v[66:69], v85 offset:43616
	ds_read_b128 v[70:73], v88 offset:34912
	global_load_dwordx4 v[74:77], v[26:27], off offset:1280 nt
	global_load_dwordx4 v[78:81], v[22:23], off offset:1280 nt
	s_waitcnt lgkmcnt(2)
	v_mfma_f32_32x32x16_bf16 v[2:17], v[34:37], v[62:65], v[2:17]
	global_load_dwordx4 v[34:37], v[24:25], off offset:1280
	s_waitcnt vmcnt(9)
	ds_write_b128 v82, v[38:41]
	s_waitcnt vmcnt(8)
	ds_write_b128 v83, v[42:45]
	s_waitcnt vmcnt(7)
	ds_write_b128 v82, v[30:33] offset:17408
	s_waitcnt vmcnt(6)
	ds_write_b128 v84, v[46:49]
	s_waitcnt vmcnt(5)
	ds_write_b128 v82, v[50:53] offset:34816
	s_waitcnt lgkmcnt(5)
	v_mfma_f32_32x32x16_bf16 v[2:17], v[66:69], v[70:73], v[2:17]
	s_waitcnt lgkmcnt(0)
	s_waitcnt lgkmcnt(0)
	s_barrier
	ds_read_b128 v[30:33], v85
	ds_read_b128 v[38:41], v86 offset:34816
	ds_read_b128 v[42:45], v85 offset:32
	ds_read_b128 v[46:49], v86 offset:34848
	s_waitcnt lgkmcnt(2)
	v_mfma_f32_32x32x16_bf16 v[2:17], v[30:33], v[38:41], v[2:17]
	ds_read_b128 v[30:33], v85 offset:64
	ds_read_b128 v[38:41], v85 offset:96
	ds_read_b128 v[50:53], v86 offset:34880
	ds_read_b128 v[62:65], v86 offset:34912
	s_waitcnt vmcnt(4)
	ds_write_b128 v82, v[54:57] offset:43520
	s_waitcnt vmcnt(3)
	ds_write_b128 v83, v[58:61] offset:43520
	s_waitcnt lgkmcnt(6)
	v_mfma_f32_32x32x16_bf16 v[2:17], v[42:45], v[46:49], v[2:17]
	global_load_dwordx4 v[42:45], v[18:19], off offset:1536 nt
	global_load_dwordx4 v[46:49], v[20:21], off offset:1536 nt
	global_load_dwordx4 v[54:57], v[26:27], off offset:1536 nt
	global_load_dwordx4 v[58:61], v[22:23], off offset:1536 nt
	global_load_dwordx4 v[66:69], v[24:25], off offset:1536
	s_waitcnt vmcnt(7)
	ds_write_b128 v82, v[74:77] offset:60928
	s_waitcnt vmcnt(6)
	ds_write_b128 v84, v[78:81] offset:43520
	s_waitcnt vmcnt(5)
	ds_write_b128 v87, v[34:37]
	s_waitcnt lgkmcnt(0)
	s_waitcnt lgkmcnt(0)
	v_mfma_f32_32x32x16_bf16 v[2:17], v[30:33], v[50:53], v[2:17]
	s_barrier
	v_mfma_f32_32x32x16_bf16 v[2:17], v[38:41], v[62:65], v[2:17]
	ds_read_b128 v[30:33], v85 offset:43520
	ds_read_b128 v[34:37], v88 offset:34816
	ds_read_b128 v[38:41], v85 offset:43552
	ds_read_b128 v[50:53], v88 offset:34848
	s_waitcnt lgkmcnt(2)
	v_mfma_f32_32x32x16_bf16 v[2:17], v[30:33], v[34:37], v[2:17]
	ds_read_b128 v[30:33], v85 offset:43584
	s_waitcnt lgkmcnt(1)
	v_mfma_f32_32x32x16_bf16 v[2:17], v[38:41], v[50:53], v[2:17]
	ds_read_b128 v[34:37], v85 offset:43616
	ds_read_b128 v[38:41], v88 offset:34880
	ds_read_b128 v[50:53], v88 offset:34912
	global_load_dwordx4 v[62:65], v[18:19], off offset:1792 nt
	s_nop 0
	global_load_dwordx4 v[18:21], v[20:21], off offset:1792 nt
	s_nop 0
	global_load_dwordx4 v[70:73], v[26:27], off offset:1792 nt
	global_load_dwordx4 v[74:77], v[22:23], off offset:1792 nt
	s_nop 0
	global_load_dwordx4 v[22:25], v[24:25], off offset:1792
	s_waitcnt vmcnt(9)
	ds_write_b128 v82, v[42:45]
	s_waitcnt vmcnt(8)
	ds_write_b128 v83, v[46:49]
	s_waitcnt vmcnt(7)
	ds_write_b128 v82, v[54:57] offset:17408
	s_waitcnt vmcnt(6)
	ds_write_b128 v84, v[58:61]
	s_waitcnt vmcnt(5)
	ds_write_b128 v82, v[66:69] offset:34816
	s_waitcnt lgkmcnt(6)
	v_mfma_f32_32x32x16_bf16 v[2:17], v[30:33], v[38:41], v[2:17]
	s_waitcnt lgkmcnt(0)
	s_waitcnt lgkmcnt(0)
	s_barrier
	v_mfma_f32_32x32x16_bf16 v[2:17], v[34:37], v[50:53], v[2:17]
	ds_read_b128 v[30:33], v85
	ds_read_b128 v[34:37], v86 offset:34816
	ds_read_b128 v[38:41], v85 offset:32
	ds_read_b128 v[42:45], v86 offset:34848
	s_waitcnt lgkmcnt(2)
	v_mfma_f32_32x32x16_bf16 v[2:17], v[30:33], v[34:37], v[2:17]
	s_waitcnt lgkmcnt(0)
	v_mfma_f32_32x32x16_bf16 v[2:17], v[38:41], v[42:45], v[2:17]
	ds_read_b128 v[30:33], v85 offset:64
	ds_read_b128 v[34:37], v86 offset:34880
	ds_read_b128 v[38:41], v85 offset:96
	ds_read_b128 v[42:45], v86 offset:34912
	s_waitcnt vmcnt(4)
	ds_write_b128 v82, v[62:65] offset:43520
	s_waitcnt vmcnt(3)
	ds_write_b128 v83, v[18:21] offset:43520
	s_waitcnt vmcnt(2)
	ds_write_b128 v82, v[70:73] offset:60928
	s_waitcnt vmcnt(1)
	ds_write_b128 v84, v[74:77] offset:43520
	s_waitcnt vmcnt(0)
	ds_write_b128 v87, v[22:25]
	s_waitcnt lgkmcnt(7)
	v_mfma_f32_32x32x16_bf16 v[2:17], v[30:33], v[34:37], v[2:17]
	s_waitcnt lgkmcnt(0)
	s_waitcnt lgkmcnt(0)
	s_barrier
	ds_read_b128 v[18:21], v85 offset:43520
	ds_read_b128 v[22:25], v88 offset:34816
	ds_read_b128 v[30:33], v85 offset:43552
	ds_read_b128 v[34:37], v88 offset:34848
	v_mfma_f32_32x32x16_bf16 v[2:17], v[38:41], v[42:45], v[2:17]
	s_waitcnt lgkmcnt(2)
	v_mfma_f32_32x32x16_bf16 v[2:17], v[18:21], v[22:25], v[2:17]
	s_waitcnt lgkmcnt(0)
	v_mfma_f32_32x32x16_bf16 v[2:17], v[30:33], v[34:37], v[2:17]
	ds_read_b128 v[18:21], v85 offset:43584
	ds_read_b128 v[22:25], v88 offset:34880
	ds_read_b128 v[30:33], v85 offset:43616
	ds_read_b128 v[34:37], v88 offset:34912
	s_waitcnt lgkmcnt(0)
	s_waitcnt lgkmcnt(0)
	s_barrier
	v_mfma_f32_32x32x16_bf16 v[2:17], v[18:21], v[22:25], v[2:17]
	v_mfma_f32_32x32x16_bf16 v[2:17], v[30:33], v[34:37], v[2:17]
	s_cbranch_scc1 .LBB0_564
	s_lshl_b32 s0, s0, 12
	s_add_i32 s0, s0, 0
	v_lshl_add_u32 v18, v177, 2, s0
	s_nop 7
	ds_write2st64_b32 v18, v2, v3 offset1:1
	ds_write2st64_b32 v18, v4, v5 offset0:2 offset1:3
	ds_write2st64_b32 v18, v6, v7 offset0:4 offset1:5
	ds_write2st64_b32 v18, v8, v9 offset0:6 offset1:7
	ds_write2st64_b32 v18, v10, v11 offset0:8 offset1:9
	ds_write2st64_b32 v18, v12, v13 offset0:10 offset1:11
	ds_write2st64_b32 v18, v14, v15 offset0:12 offset1:13
	ds_write2st64_b32 v18, v16, v17 offset0:14 offset1:15
